# next unit's second A half-tile issued at epilogue entry, ahead of the unit's output stores; first k-iteration skips that load
# speedup vs baseline: 1.0003x; 1.0003x over previous
_Z4mega6Params:
	s_mov_b32 s100, 0
	s_mov_b32 s101, 0
	v_and_b32_e32 v2, 63, v0
	s_mov_b32 s33, s2
	v_and_b32_e32 v1, 0x3ff, v0
	v_cmp_eq_u32_e32 vcc, 0, v2
	s_and_saveexec_b64 s[2:3], vcc
	s_cbranch_execz .LBB0_2
	s_getreg_b32 s4, hwreg(HW_REG_HW_ID, 0, 6)
	s_lshl_b32 s4, s4, 2
	s_and_b32 s4, s4, 0xfc
	s_add_i32 s4, s4, 0
	s_add_i32 s4, s4, 0x21100
	v_lshrrev_b32_e32 v2, 6, v1
	v_mov_b32_e32 v3, s4
	ds_write_b32 v3, v2

.LBB0_372:
	s_add_u32 s8, s6, 0xfff80080
	s_addc_u32 s9, s7, -1
	s_add_i32 s21, 0, 0x10000
	v_add_u32_e32 v143, s21, v167
	ds_read_b128 v[148:151], v143
	ds_read_b128 v[152:155], v143 offset:1024
	ds_read_b128 v[156:159], v143 offset:2048
	ds_read_b128 v[160:163], v143 offset:3072
	s_cmp_eq_u32 s20, 28
	s_cselect_b32 s11, s17, s9
	s_cselect_b32 s10, s16, s8
	s_cselect_b32 s9, s19, s15
	s_cselect_b32 s8, s18, s13
	s_add_i32 s24, 0, 0x14000
	v_add_u32_e32 v143, s24, v167
	ds_read_b128 v[208:211], v143
	ds_read_b128 v[212:215], v143 offset:1024
	ds_read_b128 v[216:219], v143 offset:2048
	ds_read_b128 v[220:223], v143 offset:3072
	s_cmp_eq_u32 s100, 1
	s_cbranch_scc1 .Lx1_skipa
	v_lshl_add_u64 v[164:165], s[6:7], 0, v[138:139]
	s_add_i32 m0, s40, 0xc000
.Lx1_skipa:
	ds_read_b128 v[172:175], v171
	ds_read_b128 v[180:183], v171 offset:1024
	ds_read_b128 v[184:187], v171 offset:2048
	ds_read_b128 v[188:191], v171 offset:3072
	ds_read_b128 v[192:195], v171 offset:4096
	ds_read_b128 v[196:199], v171 offset:5120
	ds_read_b128 v[200:203], v171 offset:6144
	ds_read_b128 v[204:207], v171 offset:7168
	s_cmp_eq_u32 s100, 1
	s_cbranch_scc1 .Lx1_skipb
	global_load_lds_dwordx4 v[164:165], off
	v_lshl_add_u64 v[164:165], s[6:7], 0, v[140:141]
	s_add_i32 m0, s40, 0xe000
	s_nop 0
	global_load_lds_dwordx4 v[164:165], off
.Lx1_skipb:
	s_waitcnt lgkmcnt(0)
	s_barrier
	s_setprio 1
	v_mfma_f32_16x16x32_bf16 v[126:129], v[148:151], v[172:175], v[126:129]
	v_mfma_f32_16x16x32_bf16 v[122:125], v[156:159], v[172:175], v[122:125]
	v_mfma_f32_16x16x32_bf16 v[110:113], v[148:151], v[184:187], v[110:113]
	v_mfma_f32_16x16x32_bf16 v[106:109], v[156:159], v[184:187], v[106:109]
	v_mfma_f32_16x16x32_bf16 v[94:97], v[148:151], v[192:195], v[94:97]
	v_mfma_f32_16x16x32_bf16 v[90:93], v[156:159], v[192:195], v[90:93]
	v_mfma_f32_16x16x32_bf16 v[78:81], v[148:151], v[200:203], v[78:81]
	v_mfma_f32_16x16x32_bf16 v[74:77], v[156:159], v[200:203], v[74:77]
	v_mfma_f32_16x16x32_bf16 v[126:129], v[152:155], v[180:183], v[126:129]
	v_mfma_f32_16x16x32_bf16 v[122:125], v[160:163], v[180:183], v[122:125]
	v_mfma_f32_16x16x32_bf16 v[110:113], v[152:155], v[188:191], v[110:113]
	v_mfma_f32_16x16x32_bf16 v[106:109], v[160:163], v[188:191], v[106:109]
	v_mfma_f32_16x16x32_bf16 v[94:97], v[152:155], v[196:199], v[94:97]
	v_mfma_f32_16x16x32_bf16 v[90:93], v[160:163], v[196:199], v[90:93]
	v_mfma_f32_16x16x32_bf16 v[78:81], v[152:155], v[204:207], v[78:81]
	v_mfma_f32_16x16x32_bf16 v[74:77], v[160:163], v[204:207], v[74:77]
	v_mfma_f32_16x16x32_bf16 v[118:121], v[208:211], v[172:175], v[118:121]
	v_mfma_f32_16x16x32_bf16 v[114:117], v[216:219], v[172:175], v[114:117]
	v_mfma_f32_16x16x32_bf16 v[102:105], v[208:211], v[184:187], v[102:105]
	v_mfma_f32_16x16x32_bf16 v[98:101], v[216:219], v[184:187], v[98:101]
	v_mfma_f32_16x16x32_bf16 v[86:89], v[208:211], v[192:195], v[86:89]
	v_mfma_f32_16x16x32_bf16 v[82:85], v[216:219], v[192:195], v[82:85]
	v_mfma_f32_16x16x32_bf16 v[70:73], v[208:211], v[200:203], v[70:73]
	v_mfma_f32_16x16x32_bf16 v[66:69], v[216:219], v[200:203], v[66:69]
	v_mfma_f32_16x16x32_bf16 v[118:121], v[212:215], v[180:183], v[118:121]
	v_mfma_f32_16x16x32_bf16 v[114:117], v[220:223], v[180:183], v[114:117]
	v_mfma_f32_16x16x32_bf16 v[102:105], v[212:215], v[188:191], v[102:105]
	v_mfma_f32_16x16x32_bf16 v[98:101], v[220:223], v[188:191], v[98:101]
	v_mfma_f32_16x16x32_bf16 v[86:89], v[212:215], v[196:199], v[86:89]
	v_mfma_f32_16x16x32_bf16 v[82:85], v[220:223], v[196:199], v[82:85]
	v_mfma_f32_16x16x32_bf16 v[70:73], v[212:215], v[204:207], v[70:73]
	v_mfma_f32_16x16x32_bf16 v[66:69], v[220:223], v[204:207], v[66:69]
	s_setprio 0
	s_mov_b32 m0, s40
	v_lshl_add_u64 v[224:225], s[10:11], 0, v[136:137]
	s_barrier
	ds_read_b128 v[172:175], v171 offset:16384
	ds_read_b128 v[180:183], v171 offset:17408
	ds_read_b128 v[184:187], v171 offset:18432
	ds_read_b128 v[188:191], v171 offset:19456
	ds_read_b128 v[192:195], v171 offset:20480
	ds_read_b128 v[196:199], v171 offset:21504
	ds_read_b128 v[200:203], v171 offset:22528
	ds_read_b128 v[204:207], v171 offset:23552
	s_add_i32 s21, s21, s39
	v_lshl_add_u64 v[164:165], s[8:9], 0, v[134:135]
	s_mov_b32 m0, s21
	s_nop 0
	global_load_lds_dwordx4 v[164:165], off
	v_lshl_add_u64 v[176:177], s[8:9], 0, v[130:131]
	s_add_i32 m0, s21, 0x2000
	s_nop 0
	global_load_lds_dwordx4 v[176:177], off
	s_mov_b32 m0, s40
	s_nop 0
	global_load_lds_dwordx4 v[224:225], off
	v_lshl_add_u64 v[236:237], s[10:11], 0, v[132:133]
	s_mov_b32 m0, s41
	s_nop 0
	global_load_lds_dwordx4 v[236:237], off
	s_add_u32 s22, s8, 0x80000
	s_addc_u32 s23, s9, 0
	s_add_i32 s21, s24, s39
	s_mov_b32 m0, s21
	s_nop 0
	global_load_lds_dwordx4 v134, s[22:23]
	s_add_i32 m0, s21, 0x2000
	s_nop 0
	global_load_lds_dwordx4 v130, s[22:23]
	s_cmp_eq_u32 s101, 1
	s_cbranch_scc1 .Lx1_w22
	s_waitcnt vmcnt(6)
	s_branch .Lx1_wj
.Lx1_w22:
	s_waitcnt vmcnt(22)
.Lx1_wj:
	s_mov_b32 s100, 0
	s_mov_b32 s101, 0
	s_waitcnt lgkmcnt(0)
	s_barrier
	s_setprio 1
	v_mfma_f32_16x16x32_bf16 v[62:65], v[148:151], v[172:175], v[62:65]
	v_mfma_f32_16x16x32_bf16 v[58:61], v[156:159], v[172:175], v[58:61]
	v_mfma_f32_16x16x32_bf16 v[46:49], v[148:151], v[184:187], v[46:49]
	v_mfma_f32_16x16x32_bf16 v[42:45], v[156:159], v[184:187], v[42:45]
	v_mfma_f32_16x16x32_bf16 v[28:31], v[148:151], v[192:195], v[28:31]
	v_mfma_f32_16x16x32_bf16 v[24:27], v[156:159], v[192:195], v[24:27]
	v_mfma_f32_16x16x32_bf16 v[12:15], v[148:151], v[200:203], v[12:15]
	v_mfma_f32_16x16x32_bf16 v[8:11], v[156:159], v[200:203], v[8:11]
	v_mfma_f32_16x16x32_bf16 v[62:65], v[152:155], v[180:183], v[62:65]
	v_mfma_f32_16x16x32_bf16 v[58:61], v[160:163], v[180:183], v[58:61]
	v_mfma_f32_16x16x32_bf16 v[46:49], v[152:155], v[188:191], v[46:49]
	v_mfma_f32_16x16x32_bf16 v[42:45], v[160:163], v[188:191], v[42:45]
	v_mfma_f32_16x16x32_bf16 v[28:31], v[152:155], v[196:199], v[28:31]
	v_mfma_f32_16x16x32_bf16 v[24:27], v[160:163], v[196:199], v[24:27]
	v_mfma_f32_16x16x32_bf16 v[12:15], v[152:155], v[204:207], v[12:15]
	v_mfma_f32_16x16x32_bf16 v[8:11], v[160:163], v[204:207], v[8:11]
	v_mfma_f32_16x16x32_bf16 v[54:57], v[208:211], v[172:175], v[54:57]
	v_mfma_f32_16x16x32_bf16 v[50:53], v[216:219], v[172:175], v[50:53]
	v_mfma_f32_16x16x32_bf16 v[38:41], v[208:211], v[184:187], v[38:41]
	v_mfma_f32_16x16x32_bf16 v[34:37], v[216:219], v[184:187], v[34:37]
	v_mfma_f32_16x16x32_bf16 v[20:23], v[208:211], v[192:195], v[20:23]
	v_mfma_f32_16x16x32_bf16 v[16:19], v[216:219], v[192:195], v[16:19]
	v_mfma_f32_16x16x32_bf16 v[4:7], v[208:211], v[200:203], v[4:7]
	v_mfma_f32_16x16x32_bf16 v[0:3], v[216:219], v[200:203], v[0:3]
	v_mfma_f32_16x16x32_bf16 v[54:57], v[212:215], v[180:183], v[54:57]
	v_mfma_f32_16x16x32_bf16 v[50:53], v[220:223], v[180:183], v[50:53]
	v_mfma_f32_16x16x32_bf16 v[38:41], v[212:215], v[188:191], v[38:41]
	v_mfma_f32_16x16x32_bf16 v[34:37], v[220:223], v[188:191], v[34:37]
	v_mfma_f32_16x16x32_bf16 v[20:23], v[212:215], v[196:199], v[20:23]
	v_mfma_f32_16x16x32_bf16 v[16:19], v[220:223], v[196:199], v[16:19]
	v_mfma_f32_16x16x32_bf16 v[4:7], v[212:215], v[204:207], v[4:7]
	v_mfma_f32_16x16x32_bf16 v[0:3], v[220:223], v[204:207], v[0:3]
	s_setprio 0
	s_add_i32 s21, 0, 0x18000
	v_add_u32_e32 v143, s21, v167
	s_barrier
	ds_read_b128 v[148:151], v143
	ds_read_b128 v[152:155], v143 offset:1024
	ds_read_b128 v[156:159], v143 offset:2048
	ds_read_b128 v[160:163], v143 offset:3072
	s_add_u32 s10, s10, 0x80000
	s_addc_u32 s11, s11, 0
	s_add_i32 s22, 0, 0x1c000
	v_add_u32_e32 v143, s22, v167
	ds_read_b128 v[208:211], v143
	ds_read_b128 v[212:215], v143 offset:1024
	ds_read_b128 v[216:219], v143 offset:2048
	ds_read_b128 v[220:223], v143 offset:3072
	s_mov_b32 m0, s42
	s_nop 0
	global_load_lds_dwordx4 v136, s[10:11]
	ds_read_b128 v[172:175], v171 offset:32768
	ds_read_b128 v[180:183], v171 offset:33792
	ds_read_b128 v[184:187], v171 offset:34816
	ds_read_b128 v[188:191], v171 offset:35840
	ds_read_b128 v[192:195], v171 offset:36864
	ds_read_b128 v[196:199], v171 offset:37888
	ds_read_b128 v[200:203], v171 offset:38912
	ds_read_b128 v[204:207], v171 offset:39936
	s_mov_b32 m0, s43
	s_nop 0
	global_load_lds_dwordx4 v132, s[10:11]
	s_waitcnt lgkmcnt(0)
	s_barrier
	s_setprio 1
	v_mfma_f32_16x16x32_bf16 v[126:129], v[148:151], v[172:175], v[126:129]
	v_mfma_f32_16x16x32_bf16 v[122:125], v[156:159], v[172:175], v[122:125]
	v_mfma_f32_16x16x32_bf16 v[110:113], v[148:151], v[184:187], v[110:113]
	v_mfma_f32_16x16x32_bf16 v[106:109], v[156:159], v[184:187], v[106:109]
	v_mfma_f32_16x16x32_bf16 v[94:97], v[148:151], v[192:195], v[94:97]
	v_mfma_f32_16x16x32_bf16 v[90:93], v[156:159], v[192:195], v[90:93]
	v_mfma_f32_16x16x32_bf16 v[78:81], v[148:151], v[200:203], v[78:81]
	v_mfma_f32_16x16x32_bf16 v[74:77], v[156:159], v[200:203], v[74:77]
	v_mfma_f32_16x16x32_bf16 v[126:129], v[152:155], v[180:183], v[126:129]
	v_mfma_f32_16x16x32_bf16 v[122:125], v[160:163], v[180:183], v[122:125]
	v_mfma_f32_16x16x32_bf16 v[110:113], v[152:155], v[188:191], v[110:113]
	v_mfma_f32_16x16x32_bf16 v[106:109], v[160:163], v[188:191], v[106:109]
	v_mfma_f32_16x16x32_bf16 v[94:97], v[152:155], v[196:199], v[94:97]
	v_mfma_f32_16x16x32_bf16 v[90:93], v[160:163], v[196:199], v[90:93]
	v_mfma_f32_16x16x32_bf16 v[78:81], v[152:155], v[204:207], v[78:81]
	v_mfma_f32_16x16x32_bf16 v[74:77], v[160:163], v[204:207], v[74:77]
	v_mfma_f32_16x16x32_bf16 v[118:121], v[208:211], v[172:175], v[118:121]
	v_mfma_f32_16x16x32_bf16 v[114:117], v[216:219], v[172:175], v[114:117]
	v_mfma_f32_16x16x32_bf16 v[102:105], v[208:211], v[184:187], v[102:105]
	v_mfma_f32_16x16x32_bf16 v[98:101], v[216:219], v[184:187], v[98:101]
	v_mfma_f32_16x16x32_bf16 v[86:89], v[208:211], v[192:195], v[86:89]
	v_mfma_f32_16x16x32_bf16 v[82:85], v[216:219], v[192:195], v[82:85]
	v_mfma_f32_16x16x32_bf16 v[70:73], v[208:211], v[200:203], v[70:73]
	v_mfma_f32_16x16x32_bf16 v[66:69], v[216:219], v[200:203], v[66:69]
	v_mfma_f32_16x16x32_bf16 v[118:121], v[212:215], v[180:183], v[118:121]
	v_mfma_f32_16x16x32_bf16 v[114:117], v[220:223], v[180:183], v[114:117]
	v_mfma_f32_16x16x32_bf16 v[102:105], v[212:215], v[188:191], v[102:105]
	v_mfma_f32_16x16x32_bf16 v[98:101], v[220:223], v[188:191], v[98:101]
	v_mfma_f32_16x16x32_bf16 v[86:89], v[212:215], v[196:199], v[86:89]
	v_mfma_f32_16x16x32_bf16 v[82:85], v[220:223], v[196:199], v[82:85]
	v_mfma_f32_16x16x32_bf16 v[70:73], v[212:215], v[204:207], v[70:73]
	v_mfma_f32_16x16x32_bf16 v[66:69], v[220:223], v[204:207], v[66:69]
	s_setprio 0
	s_barrier
	ds_read_b128 v[172:175], v171 offset:49152
	ds_read_b128 v[180:183], v171 offset:50176
	ds_read_b128 v[184:187], v171 offset:51200
	ds_read_b128 v[188:191], v171 offset:52224
	ds_read_b128 v[192:195], v171 offset:53248
	ds_read_b128 v[196:199], v171 offset:54272
	ds_read_b128 v[200:203], v171 offset:55296
	ds_read_b128 v[204:207], v171 offset:56320
	s_add_i32 s11, s21, s39
	v_lshl_add_u64 v[164:165], v[164:165], 0, s[88:89]
	s_mov_b32 m0, s11
	s_nop 0
	global_load_lds_dwordx4 v[164:165], off
	v_lshl_add_u64 v[164:165], v[176:177], 0, s[88:89]
	s_add_i32 m0, s11, 0x2000
	s_nop 0
	global_load_lds_dwordx4 v[164:165], off
	s_mov_b32 m0, s46
	v_lshl_add_u64 v[164:165], v[224:225], 0, s[88:89]
	s_nop 0
	global_load_lds_dwordx4 v[164:165], off
	v_lshl_add_u64 v[164:165], v[236:237], 0, s[88:89]
	s_mov_b32 m0, s47
	s_nop 0
	global_load_lds_dwordx4 v[164:165], off
	s_add_u32 s8, s8, 0x80080
	s_addc_u32 s9, s9, 0
	s_add_i32 s10, s39, 0x1c000
	s_mov_b32 m0, s10
	s_nop 0
	global_load_lds_dwordx4 v134, s[8:9]
	s_add_i32 m0, s10, 0x2000
	s_nop 0
	global_load_lds_dwordx4 v130, s[8:9]
	s_waitcnt vmcnt(6)
	s_waitcnt lgkmcnt(0)
	s_barrier
	s_setprio 1
	v_mfma_f32_16x16x32_bf16 v[62:65], v[148:151], v[172:175], v[62:65]
	v_mfma_f32_16x16x32_bf16 v[58:61], v[156:159], v[172:175], v[58:61]
	v_mfma_f32_16x16x32_bf16 v[46:49], v[148:151], v[184:187], v[46:49]
	v_mfma_f32_16x16x32_bf16 v[42:45], v[156:159], v[184:187], v[42:45]
	v_mfma_f32_16x16x32_bf16 v[28:31], v[148:151], v[192:195], v[28:31]
	v_mfma_f32_16x16x32_bf16 v[24:27], v[156:159], v[192:195], v[24:27]
	v_mfma_f32_16x16x32_bf16 v[12:15], v[148:151], v[200:203], v[12:15]
	v_mfma_f32_16x16x32_bf16 v[8:11], v[156:159], v[200:203], v[8:11]
	v_mfma_f32_16x16x32_bf16 v[62:65], v[152:155], v[180:183], v[62:65]
	v_mfma_f32_16x16x32_bf16 v[58:61], v[160:163], v[180:183], v[58:61]
	v_mfma_f32_16x16x32_bf16 v[46:49], v[152:155], v[188:191], v[46:49]
	v_mfma_f32_16x16x32_bf16 v[42:45], v[160:163], v[188:191], v[42:45]
	v_mfma_f32_16x16x32_bf16 v[28:31], v[152:155], v[196:199], v[28:31]
	v_mfma_f32_16x16x32_bf16 v[24:27], v[160:163], v[196:199], v[24:27]
	v_mfma_f32_16x16x32_bf16 v[12:15], v[152:155], v[204:207], v[12:15]
	v_mfma_f32_16x16x32_bf16 v[8:11], v[160:163], v[204:207], v[8:11]
	v_mfma_f32_16x16x32_bf16 v[54:57], v[208:211], v[172:175], v[54:57]
	v_mfma_f32_16x16x32_bf16 v[50:53], v[216:219], v[172:175], v[50:53]
	v_mfma_f32_16x16x32_bf16 v[38:41], v[208:211], v[184:187], v[38:41]
	v_mfma_f32_16x16x32_bf16 v[34:37], v[216:219], v[184:187], v[34:37]
	v_mfma_f32_16x16x32_bf16 v[20:23], v[208:211], v[192:195], v[20:23]
	v_mfma_f32_16x16x32_bf16 v[16:19], v[216:219], v[192:195], v[16:19]
	v_mfma_f32_16x16x32_bf16 v[4:7], v[208:211], v[200:203], v[4:7]
	v_mfma_f32_16x16x32_bf16 v[0:3], v[216:219], v[200:203], v[0:3]
	v_mfma_f32_16x16x32_bf16 v[54:57], v[212:215], v[180:183], v[54:57]
	v_mfma_f32_16x16x32_bf16 v[50:53], v[220:223], v[180:183], v[50:53]
	v_mfma_f32_16x16x32_bf16 v[38:41], v[212:215], v[188:191], v[38:41]
	v_mfma_f32_16x16x32_bf16 v[34:37], v[220:223], v[188:191], v[34:37]
	v_mfma_f32_16x16x32_bf16 v[20:23], v[212:215], v[196:199], v[20:23]
	v_mfma_f32_16x16x32_bf16 v[16:19], v[220:223], v[196:199], v[16:19]
	v_mfma_f32_16x16x32_bf16 v[4:7], v[212:215], v[204:207], v[4:7]
	v_mfma_f32_16x16x32_bf16 v[0:3], v[220:223], v[204:207], v[0:3]
	s_setprio 0
	s_add_i32 s20, s20, 2
	s_add_u32 s6, s6, 0x100
	s_addc_u32 s7, s7, 0
	s_add_u32 s13, s13, 0x100
	s_addc_u32 s15, s15, 0
	s_cmp_gt_u32 s20, 29
	s_barrier
	s_cbranch_scc0 .LBB0_372
	s_and_b64 s[6:7], exec, s[4:5]
	s_cbranch_scc1 .Lx1_none
	s_add_u32 s6, s16, 0x80080
	s_addc_u32 s7, s17, 0
	s_add_i32 m0, s40, 0xc000
	s_nop 0
	global_load_lds_dwordx4 v138, s[6:7]
	s_add_i32 m0, s40, 0xe000
	s_nop 0
	global_load_lds_dwordx4 v140, s[6:7]
	s_mov_b32 s100, 1
.Lx1_none:
	s_sub_i32 s6, s51, 8
	s_cmp_lt_u32 s6, 8
	s_cbranch_scc1 .Lmain_old
	s_sub_i32 s6, s51, 32
	s_cmp_lt_u32 s6, 12
	s_cbranch_scc1 .Lmain_kv
	v_mbcnt_lo_u32_b32 v217, -1, 0
	v_mbcnt_hi_u32_b32 v217, -1, v217
	v_lshrrev_b32_e32 v208, 4, v217
	v_bfe_u32 v209, v217, 2, 2
	v_and_b32_e32 v210, 3, v217
	v_lshl_add_u32 v235, v208, 2, v209
	v_lshl_add_u32 v217, v210, 4, v235
	v_lshlrev_b32_e32 v217, 2, v217
	v_add_u32_e32 v235, s45, v235
	v_lshlrev_b32_e32 v210, 4, v210
	s_lshl_b32 s6, s44, 6
	v_add_u32_e32 v210, s6, v210
	s_cmp_ge_u32 s51, 0x44
	s_cbranch_scc1 .Lmain_sig
	s_sub_i32 s6, s51, 44
	s_mov_b32 s7, 0x25e51000
	s_mov_b32 s13, 0x15e51000
	s_cmp_lt_i32 s6, 0
	s_cselect_b32 s6, s51, s6
	s_cselect_b32 s7, s13, s7
	s_lshr_b32 s13, s6, 3
	s_lshl_b32 s13, s13, 26
	s_add_i32 s7, s7, s13
	s_and_b32 s6, s6, 7
	s_lshl_b32 s6, s6, 9
	s_add_i32 s7, s7, s6
	s_lshl_b32 s6, s31, 20
	s_add_i32 s7, s7, s6
	s_add_u32 s22, s76, s7
	s_addc_u32 s23, s77, 0
	v_lshl_add_u32 v235, v235, 12, v210
	s_lshr_b32 s6, s51, 3
	s_cmp_eq_u32 s6, 3
	s_cbranch_scc1 .Lmain_q
	s_add_u32 s10, s22, 0
	s_addc_u32 s11, s23, 0
	v_cvt_pk_bf16_f32 v148, v126, v127
	v_cvt_pk_bf16_f32 v149, v128, v129
	v_cvt_pk_bf16_f32 v150, v122, v123
	v_cvt_pk_bf16_f32 v151, v124, v125
	ds_bpermute_b32 v238, v217, v148
	ds_bpermute_b32 v239, v217, v149
	ds_bpermute_b32 v240, v217, v150
	ds_bpermute_b32 v241, v217, v151
	v_cvt_pk_bf16_f32 v152, v118, v119
	v_cvt_pk_bf16_f32 v153, v120, v121
	v_cvt_pk_bf16_f32 v154, v114, v115
	v_cvt_pk_bf16_f32 v155, v116, v117
	ds_bpermute_b32 v242, v217, v152
	ds_bpermute_b32 v243, v217, v153
	ds_bpermute_b32 v244, v217, v154
	ds_bpermute_b32 v245, v217, v155
	s_add_u32 s20, s22, 0x10000
	s_addc_u32 s21, s23, 0
	v_cvt_pk_bf16_f32 v156, v110, v111
	v_cvt_pk_bf16_f32 v157, v112, v113
	v_cvt_pk_bf16_f32 v158, v106, v107
	v_cvt_pk_bf16_f32 v159, v108, v109
	ds_bpermute_b32 v246, v217, v156
	ds_bpermute_b32 v247, v217, v157
	ds_bpermute_b32 v248, v217, v158
	ds_bpermute_b32 v249, v217, v159
	v_cvt_pk_bf16_f32 v160, v102, v103
	v_cvt_pk_bf16_f32 v161, v104, v105
	v_cvt_pk_bf16_f32 v162, v98, v99
	v_cvt_pk_bf16_f32 v163, v100, v101
	ds_bpermute_b32 v250, v217, v160
	ds_bpermute_b32 v251, v217, v161
	ds_bpermute_b32 v252, v217, v162
	ds_bpermute_b32 v253, v217, v163
	s_waitcnt lgkmcnt(0)
	global_store_dwordx4 v235, v[238:241], s[10:11] sc0 sc1
	global_store_dwordx4 v235, v[242:245], s[10:11] offset:256 sc0 sc1
	global_store_dwordx4 v235, v[246:249], s[20:21] sc0 sc1
	global_store_dwordx4 v235, v[250:253], s[20:21] offset:256 sc0 sc1
	s_add_u32 s10, s22, 0x20000
	s_addc_u32 s11, s23, 0
	v_cvt_pk_bf16_f32 v148, v94, v95
	v_cvt_pk_bf16_f32 v149, v96, v97
	v_cvt_pk_bf16_f32 v150, v90, v91
	v_cvt_pk_bf16_f32 v151, v92, v93
	ds_bpermute_b32 v238, v217, v148
	ds_bpermute_b32 v239, v217, v149
	ds_bpermute_b32 v240, v217, v150
	ds_bpermute_b32 v241, v217, v151
	v_cvt_pk_bf16_f32 v152, v86, v87
	v_cvt_pk_bf16_f32 v153, v88, v89
	v_cvt_pk_bf16_f32 v154, v82, v83
	v_cvt_pk_bf16_f32 v155, v84, v85
	ds_bpermute_b32 v242, v217, v152
	ds_bpermute_b32 v243, v217, v153
	ds_bpermute_b32 v244, v217, v154
	ds_bpermute_b32 v245, v217, v155
	s_add_u32 s20, s22, 0x30000
	s_addc_u32 s21, s23, 0
	v_cvt_pk_bf16_f32 v156, v78, v79
	v_cvt_pk_bf16_f32 v157, v80, v81
	v_cvt_pk_bf16_f32 v158, v74, v75
	v_cvt_pk_bf16_f32 v159, v76, v77
	ds_bpermute_b32 v246, v217, v156
	ds_bpermute_b32 v247, v217, v157
	ds_bpermute_b32 v248, v217, v158
	ds_bpermute_b32 v249, v217, v159
	v_cvt_pk_bf16_f32 v160, v70, v71
	v_cvt_pk_bf16_f32 v161, v72, v73
	v_cvt_pk_bf16_f32 v162, v66, v67
	v_cvt_pk_bf16_f32 v163, v68, v69
	ds_bpermute_b32 v250, v217, v160
	ds_bpermute_b32 v251, v217, v161
	ds_bpermute_b32 v252, v217, v162
	ds_bpermute_b32 v253, v217, v163
	s_waitcnt lgkmcnt(0)
	global_store_dwordx4 v235, v[238:241], s[10:11] sc0 sc1
	global_store_dwordx4 v235, v[242:245], s[10:11] offset:256 sc0 sc1
	global_store_dwordx4 v235, v[246:249], s[20:21] sc0 sc1
	global_store_dwordx4 v235, v[250:253], s[20:21] offset:256 sc0 sc1
	s_add_u32 s10, s22, 0x80000
	s_addc_u32 s11, s23, 0
	v_cvt_pk_bf16_f32 v148, v62, v63
	v_cvt_pk_bf16_f32 v149, v64, v65
	v_cvt_pk_bf16_f32 v150, v58, v59
	v_cvt_pk_bf16_f32 v151, v60, v61
	ds_bpermute_b32 v238, v217, v148
	ds_bpermute_b32 v239, v217, v149
	ds_bpermute_b32 v240, v217, v150
	ds_bpermute_b32 v241, v217, v151
	v_cvt_pk_bf16_f32 v152, v54, v55
	v_cvt_pk_bf16_f32 v153, v56, v57
	v_cvt_pk_bf16_f32 v154, v50, v51
	v_cvt_pk_bf16_f32 v155, v52, v53
	ds_bpermute_b32 v242, v217, v152
	ds_bpermute_b32 v243, v217, v153
	ds_bpermute_b32 v244, v217, v154
	ds_bpermute_b32 v245, v217, v155
	s_add_u32 s20, s22, 0x90000
	s_addc_u32 s21, s23, 0
	v_cvt_pk_bf16_f32 v156, v46, v47
	v_cvt_pk_bf16_f32 v157, v48, v49
	v_cvt_pk_bf16_f32 v158, v42, v43
	v_cvt_pk_bf16_f32 v159, v44, v45
	ds_bpermute_b32 v246, v217, v156
	ds_bpermute_b32 v247, v217, v157
	ds_bpermute_b32 v248, v217, v158
	ds_bpermute_b32 v249, v217, v159
	v_cvt_pk_bf16_f32 v160, v38, v39
	v_cvt_pk_bf16_f32 v161, v40, v41
	v_cvt_pk_bf16_f32 v162, v34, v35
	v_cvt_pk_bf16_f32 v163, v36, v37
	ds_bpermute_b32 v250, v217, v160
	ds_bpermute_b32 v251, v217, v161
	ds_bpermute_b32 v252, v217, v162
	ds_bpermute_b32 v253, v217, v163
	s_waitcnt lgkmcnt(0)
	global_store_dwordx4 v235, v[238:241], s[10:11] sc0 sc1
	global_store_dwordx4 v235, v[242:245], s[10:11] offset:256 sc0 sc1
	global_store_dwordx4 v235, v[246:249], s[20:21] sc0 sc1
	global_store_dwordx4 v235, v[250:253], s[20:21] offset:256 sc0 sc1
	s_add_u32 s10, s22, 0xa0000
	s_addc_u32 s11, s23, 0
	v_cvt_pk_bf16_f32 v148, v28, v29
	v_cvt_pk_bf16_f32 v149, v30, v31
	v_cvt_pk_bf16_f32 v150, v24, v25
	v_cvt_pk_bf16_f32 v151, v26, v27
	ds_bpermute_b32 v238, v217, v148
	ds_bpermute_b32 v239, v217, v149
	ds_bpermute_b32 v240, v217, v150
	ds_bpermute_b32 v241, v217, v151
	v_cvt_pk_bf16_f32 v152, v20, v21
	v_cvt_pk_bf16_f32 v153, v22, v23
	v_cvt_pk_bf16_f32 v154, v16, v17
	v_cvt_pk_bf16_f32 v155, v18, v19
	ds_bpermute_b32 v242, v217, v152
	ds_bpermute_b32 v243, v217, v153
	ds_bpermute_b32 v244, v217, v154
	ds_bpermute_b32 v245, v217, v155
	s_add_u32 s20, s22, 0xb0000
	s_addc_u32 s21, s23, 0
	v_cvt_pk_bf16_f32 v156, v12, v13
	v_cvt_pk_bf16_f32 v157, v14, v15
	v_cvt_pk_bf16_f32 v158, v8, v9
	v_cvt_pk_bf16_f32 v159, v10, v11
	ds_bpermute_b32 v246, v217, v156
	ds_bpermute_b32 v247, v217, v157
	ds_bpermute_b32 v248, v217, v158
	ds_bpermute_b32 v249, v217, v159
	v_cvt_pk_bf16_f32 v160, v4, v5
	v_cvt_pk_bf16_f32 v161, v6, v7
	v_cvt_pk_bf16_f32 v162, v0, v1
	v_cvt_pk_bf16_f32 v163, v2, v3
	ds_bpermute_b32 v250, v217, v160
	ds_bpermute_b32 v251, v217, v161
	ds_bpermute_b32 v252, v217, v162
	ds_bpermute_b32 v253, v217, v163
	s_waitcnt lgkmcnt(0)
	global_store_dwordx4 v235, v[238:241], s[10:11] sc0 sc1
	global_store_dwordx4 v235, v[242:245], s[10:11] offset:256 sc0 sc1
	global_store_dwordx4 v235, v[246:249], s[20:21] sc0 sc1
	global_store_dwordx4 v235, v[250:253], s[20:21] offset:256 sc0 sc1
	s_mov_b32 s101, 0
	s_branch .Lmain_latch_fast
.Lmain_q:
	s_mov_b32 s6, 0x3e0293ee
	s_add_u32 s10, s22, 0
	s_addc_u32 s11, s23, 0
	v_pk_mul_f32 v[126:127], v[126:127], s[6:7] op_sel_hi:[1,0]
	v_pk_mul_f32 v[128:129], v[128:129], s[6:7] op_sel_hi:[1,0]
	v_pk_mul_f32 v[122:123], v[122:123], s[6:7] op_sel_hi:[1,0]
	v_pk_mul_f32 v[124:125], v[124:125], s[6:7] op_sel_hi:[1,0]
	v_cvt_pk_bf16_f32 v148, v126, v127
	v_cvt_pk_bf16_f32 v149, v128, v129
	v_cvt_pk_bf16_f32 v150, v122, v123
	v_cvt_pk_bf16_f32 v151, v124, v125
	ds_bpermute_b32 v238, v217, v148
	ds_bpermute_b32 v239, v217, v149
	ds_bpermute_b32 v240, v217, v150
	ds_bpermute_b32 v241, v217, v151
	v_pk_mul_f32 v[118:119], v[118:119], s[6:7] op_sel_hi:[1,0]
	v_pk_mul_f32 v[120:121], v[120:121], s[6:7] op_sel_hi:[1,0]
	v_pk_mul_f32 v[114:115], v[114:115], s[6:7] op_sel_hi:[1,0]
	v_pk_mul_f32 v[116:117], v[116:117], s[6:7] op_sel_hi:[1,0]
	v_cvt_pk_bf16_f32 v152, v118, v119
	v_cvt_pk_bf16_f32 v153, v120, v121
	v_cvt_pk_bf16_f32 v154, v114, v115
	v_cvt_pk_bf16_f32 v155, v116, v117
	ds_bpermute_b32 v242, v217, v152
	ds_bpermute_b32 v243, v217, v153
	ds_bpermute_b32 v244, v217, v154
	ds_bpermute_b32 v245, v217, v155
	s_add_u32 s20, s22, 0x10000
	s_addc_u32 s21, s23, 0
	v_pk_mul_f32 v[110:111], v[110:111], s[6:7] op_sel_hi:[1,0]
	v_pk_mul_f32 v[112:113], v[112:113], s[6:7] op_sel_hi:[1,0]
	v_pk_mul_f32 v[106:107], v[106:107], s[6:7] op_sel_hi:[1,0]
	v_pk_mul_f32 v[108:109], v[108:109], s[6:7] op_sel_hi:[1,0]
	v_cvt_pk_bf16_f32 v156, v110, v111
	v_cvt_pk_bf16_f32 v157, v112, v113
	v_cvt_pk_bf16_f32 v158, v106, v107
	v_cvt_pk_bf16_f32 v159, v108, v109
	ds_bpermute_b32 v246, v217, v156
	ds_bpermute_b32 v247, v217, v157
	ds_bpermute_b32 v248, v217, v158
	ds_bpermute_b32 v249, v217, v159
	v_pk_mul_f32 v[102:103], v[102:103], s[6:7] op_sel_hi:[1,0]
	v_pk_mul_f32 v[104:105], v[104:105], s[6:7] op_sel_hi:[1,0]
	v_pk_mul_f32 v[98:99], v[98:99], s[6:7] op_sel_hi:[1,0]
	v_pk_mul_f32 v[100:101], v[100:101], s[6:7] op_sel_hi:[1,0]
	v_cvt_pk_bf16_f32 v160, v102, v103
	v_cvt_pk_bf16_f32 v161, v104, v105
	v_cvt_pk_bf16_f32 v162, v98, v99
	v_cvt_pk_bf16_f32 v163, v100, v101
	ds_bpermute_b32 v250, v217, v160
	ds_bpermute_b32 v251, v217, v161
	ds_bpermute_b32 v252, v217, v162
	ds_bpermute_b32 v253, v217, v163
	s_waitcnt lgkmcnt(0)
	global_store_dwordx4 v235, v[238:241], s[10:11] sc0 sc1
	global_store_dwordx4 v235, v[242:245], s[10:11] offset:256 sc0 sc1
	global_store_dwordx4 v235, v[246:249], s[20:21] sc0 sc1
	global_store_dwordx4 v235, v[250:253], s[20:21] offset:256 sc0 sc1
	s_add_u32 s10, s22, 0x20000
	s_addc_u32 s11, s23, 0
	v_pk_mul_f32 v[94:95], v[94:95], s[6:7] op_sel_hi:[1,0]
	v_pk_mul_f32 v[96:97], v[96:97], s[6:7] op_sel_hi:[1,0]
	v_pk_mul_f32 v[90:91], v[90:91], s[6:7] op_sel_hi:[1,0]
	v_pk_mul_f32 v[92:93], v[92:93], s[6:7] op_sel_hi:[1,0]
	v_cvt_pk_bf16_f32 v148, v94, v95
	v_cvt_pk_bf16_f32 v149, v96, v97
	v_cvt_pk_bf16_f32 v150, v90, v91
	v_cvt_pk_bf16_f32 v151, v92, v93
	ds_bpermute_b32 v238, v217, v148
	ds_bpermute_b32 v239, v217, v149
	ds_bpermute_b32 v240, v217, v150
	ds_bpermute_b32 v241, v217, v151
	v_pk_mul_f32 v[86:87], v[86:87], s[6:7] op_sel_hi:[1,0]
	v_pk_mul_f32 v[88:89], v[88:89], s[6:7] op_sel_hi:[1,0]
	v_pk_mul_f32 v[82:83], v[82:83], s[6:7] op_sel_hi:[1,0]
	v_pk_mul_f32 v[84:85], v[84:85], s[6:7] op_sel_hi:[1,0]
	v_cvt_pk_bf16_f32 v152, v86, v87
	v_cvt_pk_bf16_f32 v153, v88, v89
	v_cvt_pk_bf16_f32 v154, v82, v83
	v_cvt_pk_bf16_f32 v155, v84, v85
	ds_bpermute_b32 v242, v217, v152
	ds_bpermute_b32 v243, v217, v153
	ds_bpermute_b32 v244, v217, v154
	ds_bpermute_b32 v245, v217, v155
	s_add_u32 s20, s22, 0x30000
	s_addc_u32 s21, s23, 0
	v_pk_mul_f32 v[78:79], v[78:79], s[6:7] op_sel_hi:[1,0]
	v_pk_mul_f32 v[80:81], v[80:81], s[6:7] op_sel_hi:[1,0]
	v_pk_mul_f32 v[74:75], v[74:75], s[6:7] op_sel_hi:[1,0]
	v_pk_mul_f32 v[76:77], v[76:77], s[6:7] op_sel_hi:[1,0]
	v_cvt_pk_bf16_f32 v156, v78, v79
	v_cvt_pk_bf16_f32 v157, v80, v81
	v_cvt_pk_bf16_f32 v158, v74, v75
	v_cvt_pk_bf16_f32 v159, v76, v77
	ds_bpermute_b32 v246, v217, v156
	ds_bpermute_b32 v247, v217, v157
	ds_bpermute_b32 v248, v217, v158
	ds_bpermute_b32 v249, v217, v159
	v_pk_mul_f32 v[70:71], v[70:71], s[6:7] op_sel_hi:[1,0]
	v_pk_mul_f32 v[72:73], v[72:73], s[6:7] op_sel_hi:[1,0]
	v_pk_mul_f32 v[66:67], v[66:67], s[6:7] op_sel_hi:[1,0]
	v_pk_mul_f32 v[68:69], v[68:69], s[6:7] op_sel_hi:[1,0]
	v_cvt_pk_bf16_f32 v160, v70, v71
	v_cvt_pk_bf16_f32 v161, v72, v73
	v_cvt_pk_bf16_f32 v162, v66, v67
	v_cvt_pk_bf16_f32 v163, v68, v69
	ds_bpermute_b32 v250, v217, v160
	ds_bpermute_b32 v251, v217, v161
	ds_bpermute_b32 v252, v217, v162
	ds_bpermute_b32 v253, v217, v163
	s_waitcnt lgkmcnt(0)
	global_store_dwordx4 v235, v[238:241], s[10:11] sc0 sc1
	global_store_dwordx4 v235, v[242:245], s[10:11] offset:256 sc0 sc1
	global_store_dwordx4 v235, v[246:249], s[20:21] sc0 sc1
	global_store_dwordx4 v235, v[250:253], s[20:21] offset:256 sc0 sc1
	s_add_u32 s10, s22, 0x80000
	s_addc_u32 s11, s23, 0
	v_pk_mul_f32 v[62:63], v[62:63], s[6:7] op_sel_hi:[1,0]
	v_pk_mul_f32 v[64:65], v[64:65], s[6:7] op_sel_hi:[1,0]
	v_pk_mul_f32 v[58:59], v[58:59], s[6:7] op_sel_hi:[1,0]
	v_pk_mul_f32 v[60:61], v[60:61], s[6:7] op_sel_hi:[1,0]
	v_cvt_pk_bf16_f32 v148, v62, v63
	v_cvt_pk_bf16_f32 v149, v64, v65
	v_cvt_pk_bf16_f32 v150, v58, v59
	v_cvt_pk_bf16_f32 v151, v60, v61
	ds_bpermute_b32 v238, v217, v148
	ds_bpermute_b32 v239, v217, v149
	ds_bpermute_b32 v240, v217, v150
	ds_bpermute_b32 v241, v217, v151
	v_pk_mul_f32 v[54:55], v[54:55], s[6:7] op_sel_hi:[1,0]
	v_pk_mul_f32 v[56:57], v[56:57], s[6:7] op_sel_hi:[1,0]
	v_pk_mul_f32 v[50:51], v[50:51], s[6:7] op_sel_hi:[1,0]
	v_pk_mul_f32 v[52:53], v[52:53], s[6:7] op_sel_hi:[1,0]
	v_cvt_pk_bf16_f32 v152, v54, v55
	v_cvt_pk_bf16_f32 v153, v56, v57
	v_cvt_pk_bf16_f32 v154, v50, v51
	v_cvt_pk_bf16_f32 v155, v52, v53
	ds_bpermute_b32 v242, v217, v152
	ds_bpermute_b32 v243, v217, v153
	ds_bpermute_b32 v244, v217, v154
	ds_bpermute_b32 v245, v217, v155
	s_add_u32 s20, s22, 0x90000
	s_addc_u32 s21, s23, 0
	v_pk_mul_f32 v[46:47], v[46:47], s[6:7] op_sel_hi:[1,0]
	v_pk_mul_f32 v[48:49], v[48:49], s[6:7] op_sel_hi:[1,0]
	v_pk_mul_f32 v[42:43], v[42:43], s[6:7] op_sel_hi:[1,0]
	v_pk_mul_f32 v[44:45], v[44:45], s[6:7] op_sel_hi:[1,0]
	v_cvt_pk_bf16_f32 v156, v46, v47
	v_cvt_pk_bf16_f32 v157, v48, v49
	v_cvt_pk_bf16_f32 v158, v42, v43
	v_cvt_pk_bf16_f32 v159, v44, v45
	ds_bpermute_b32 v246, v217, v156
	ds_bpermute_b32 v247, v217, v157
	ds_bpermute_b32 v248, v217, v158
	ds_bpermute_b32 v249, v217, v159
	v_pk_mul_f32 v[38:39], v[38:39], s[6:7] op_sel_hi:[1,0]
	v_pk_mul_f32 v[40:41], v[40:41], s[6:7] op_sel_hi:[1,0]
	v_pk_mul_f32 v[34:35], v[34:35], s[6:7] op_sel_hi:[1,0]
	v_pk_mul_f32 v[36:37], v[36:37], s[6:7] op_sel_hi:[1,0]
	v_cvt_pk_bf16_f32 v160, v38, v39
	v_cvt_pk_bf16_f32 v161, v40, v41
	v_cvt_pk_bf16_f32 v162, v34, v35
	v_cvt_pk_bf16_f32 v163, v36, v37
	ds_bpermute_b32 v250, v217, v160
	ds_bpermute_b32 v251, v217, v161
	ds_bpermute_b32 v252, v217, v162
	ds_bpermute_b32 v253, v217, v163
	s_waitcnt lgkmcnt(0)
	global_store_dwordx4 v235, v[238:241], s[10:11] sc0 sc1
	global_store_dwordx4 v235, v[242:245], s[10:11] offset:256 sc0 sc1
	global_store_dwordx4 v235, v[246:249], s[20:21] sc0 sc1
	global_store_dwordx4 v235, v[250:253], s[20:21] offset:256 sc0 sc1
	s_add_u32 s10, s22, 0xa0000
	s_addc_u32 s11, s23, 0
	v_pk_mul_f32 v[28:29], v[28:29], s[6:7] op_sel_hi:[1,0]
	v_pk_mul_f32 v[30:31], v[30:31], s[6:7] op_sel_hi:[1,0]
	v_pk_mul_f32 v[24:25], v[24:25], s[6:7] op_sel_hi:[1,0]
	v_pk_mul_f32 v[26:27], v[26:27], s[6:7] op_sel_hi:[1,0]
	v_cvt_pk_bf16_f32 v148, v28, v29
	v_cvt_pk_bf16_f32 v149, v30, v31
	v_cvt_pk_bf16_f32 v150, v24, v25
	v_cvt_pk_bf16_f32 v151, v26, v27
	ds_bpermute_b32 v238, v217, v148
	ds_bpermute_b32 v239, v217, v149
	ds_bpermute_b32 v240, v217, v150
	ds_bpermute_b32 v241, v217, v151
	v_pk_mul_f32 v[20:21], v[20:21], s[6:7] op_sel_hi:[1,0]
	v_pk_mul_f32 v[22:23], v[22:23], s[6:7] op_sel_hi:[1,0]
	v_pk_mul_f32 v[16:17], v[16:17], s[6:7] op_sel_hi:[1,0]
	v_pk_mul_f32 v[18:19], v[18:19], s[6:7] op_sel_hi:[1,0]
	v_cvt_pk_bf16_f32 v152, v20, v21
	v_cvt_pk_bf16_f32 v153, v22, v23
	v_cvt_pk_bf16_f32 v154, v16, v17
	v_cvt_pk_bf16_f32 v155, v18, v19
	ds_bpermute_b32 v242, v217, v152
	ds_bpermute_b32 v243, v217, v153
	ds_bpermute_b32 v244, v217, v154
	ds_bpermute_b32 v245, v217, v155
	s_add_u32 s20, s22, 0xb0000
	s_addc_u32 s21, s23, 0
	v_pk_mul_f32 v[12:13], v[12:13], s[6:7] op_sel_hi:[1,0]
	v_pk_mul_f32 v[14:15], v[14:15], s[6:7] op_sel_hi:[1,0]
	v_pk_mul_f32 v[8:9], v[8:9], s[6:7] op_sel_hi:[1,0]
	v_pk_mul_f32 v[10:11], v[10:11], s[6:7] op_sel_hi:[1,0]
	v_cvt_pk_bf16_f32 v156, v12, v13
	v_cvt_pk_bf16_f32 v157, v14, v15
	v_cvt_pk_bf16_f32 v158, v8, v9
	v_cvt_pk_bf16_f32 v159, v10, v11
	ds_bpermute_b32 v246, v217, v156
	ds_bpermute_b32 v247, v217, v157
	ds_bpermute_b32 v248, v217, v158
	ds_bpermute_b32 v249, v217, v159
	v_pk_mul_f32 v[4:5], v[4:5], s[6:7] op_sel_hi:[1,0]
	v_pk_mul_f32 v[6:7], v[6:7], s[6:7] op_sel_hi:[1,0]
	v_pk_mul_f32 v[0:1], v[0:1], s[6:7] op_sel_hi:[1,0]
	v_pk_mul_f32 v[2:3], v[2:3], s[6:7] op_sel_hi:[1,0]
	v_cvt_pk_bf16_f32 v160, v4, v5
	v_cvt_pk_bf16_f32 v161, v6, v7
	v_cvt_pk_bf16_f32 v162, v0, v1
	v_cvt_pk_bf16_f32 v163, v2, v3
	ds_bpermute_b32 v250, v217, v160
	ds_bpermute_b32 v251, v217, v161
	ds_bpermute_b32 v252, v217, v162
	ds_bpermute_b32 v253, v217, v163
	s_waitcnt lgkmcnt(0)
	global_store_dwordx4 v235, v[238:241], s[10:11] sc0 sc1
	global_store_dwordx4 v235, v[242:245], s[10:11] offset:256 sc0 sc1
	global_store_dwordx4 v235, v[246:249], s[20:21] sc0 sc1
	global_store_dwordx4 v235, v[250:253], s[20:21] offset:256 sc0 sc1
	s_mov_b32 s101, 0
	s_branch .Lmain_latch_fast
.Lmain_sig:
	s_mul_i32 s7, s31, 0x300000
	s_sub_i32 s6, s51, 0x44
	s_lshl_b32 s6, s6, 9
	s_add_i32 s7, s7, s6
	s_add_i32 s7, s7, 0x37f51000
	s_add_u32 s22, s76, s7
	s_addc_u32 s23, s77, 0
	v_mul_u32_u24_e32 v235, 0x3000, v235
	v_add_u32_e32 v235, v235, v210
	s_add_u32 s10, s22, 0
	s_addc_u32 s11, s23, 0
	v_mul_f32_e32 v208, 0xbfb8aa3b, v126
	v_mul_f32_e32 v209, 0xbfb8aa3b, v127
	v_mul_f32_e32 v210, 0xbfb8aa3b, v128
	v_mul_f32_e32 v211, 0xbfb8aa3b, v129
	v_mul_f32_e32 v212, 0xbfb8aa3b, v122
	v_mul_f32_e32 v213, 0xbfb8aa3b, v123
	v_mul_f32_e32 v214, 0xbfb8aa3b, v124
	v_mul_f32_e32 v215, 0xbfb8aa3b, v125
	v_exp_f32_e32 v208, v208
	v_exp_f32_e32 v209, v209
	v_exp_f32_e32 v210, v210
	v_exp_f32_e32 v211, v211
	v_exp_f32_e32 v212, v212
	v_exp_f32_e32 v213, v213
	v_exp_f32_e32 v214, v214
	v_exp_f32_e32 v215, v215
	v_add_f32_e32 v208, 1.0, v208
	v_add_f32_e32 v209, 1.0, v209
	v_add_f32_e32 v210, 1.0, v210
	v_add_f32_e32 v211, 1.0, v211
	v_add_f32_e32 v212, 1.0, v212
	v_add_f32_e32 v213, 1.0, v213
	v_add_f32_e32 v214, 1.0, v214
	v_add_f32_e32 v215, 1.0, v215
	v_rcp_f32_e32 v208, v208
	v_rcp_f32_e32 v209, v209
	v_rcp_f32_e32 v210, v210
	v_rcp_f32_e32 v211, v211
	v_rcp_f32_e32 v212, v212
	v_rcp_f32_e32 v213, v213
	v_rcp_f32_e32 v214, v214
	v_rcp_f32_e32 v215, v215
	v_cvt_pk_bf16_f32 v148, v208, v209
	v_cvt_pk_bf16_f32 v149, v210, v211
	v_cvt_pk_bf16_f32 v150, v212, v213
	v_cvt_pk_bf16_f32 v151, v214, v215
	ds_bpermute_b32 v238, v217, v148
	ds_bpermute_b32 v239, v217, v149
	ds_bpermute_b32 v240, v217, v150
	ds_bpermute_b32 v241, v217, v151
	v_mul_f32_e32 v208, 0xbfb8aa3b, v118
	v_mul_f32_e32 v209, 0xbfb8aa3b, v119
	v_mul_f32_e32 v210, 0xbfb8aa3b, v120
	v_mul_f32_e32 v211, 0xbfb8aa3b, v121
	v_mul_f32_e32 v212, 0xbfb8aa3b, v114
	v_mul_f32_e32 v213, 0xbfb8aa3b, v115
	v_mul_f32_e32 v214, 0xbfb8aa3b, v116
	v_mul_f32_e32 v215, 0xbfb8aa3b, v117
	v_exp_f32_e32 v208, v208
	v_exp_f32_e32 v209, v209
	v_exp_f32_e32 v210, v210
	v_exp_f32_e32 v211, v211
	v_exp_f32_e32 v212, v212
	v_exp_f32_e32 v213, v213
	v_exp_f32_e32 v214, v214
	v_exp_f32_e32 v215, v215
	v_add_f32_e32 v208, 1.0, v208
	v_add_f32_e32 v209, 1.0, v209
	v_add_f32_e32 v210, 1.0, v210
	v_add_f32_e32 v211, 1.0, v211
	v_add_f32_e32 v212, 1.0, v212
	v_add_f32_e32 v213, 1.0, v213
	v_add_f32_e32 v214, 1.0, v214
	v_add_f32_e32 v215, 1.0, v215
	v_rcp_f32_e32 v208, v208
	v_rcp_f32_e32 v209, v209
	v_rcp_f32_e32 v210, v210
	v_rcp_f32_e32 v211, v211
	v_rcp_f32_e32 v212, v212
	v_rcp_f32_e32 v213, v213
	v_rcp_f32_e32 v214, v214
	v_rcp_f32_e32 v215, v215
	v_cvt_pk_bf16_f32 v152, v208, v209
	v_cvt_pk_bf16_f32 v153, v210, v211
	v_cvt_pk_bf16_f32 v154, v212, v213
	v_cvt_pk_bf16_f32 v155, v214, v215
	ds_bpermute_b32 v242, v217, v152
	ds_bpermute_b32 v243, v217, v153
	ds_bpermute_b32 v244, v217, v154
	ds_bpermute_b32 v245, v217, v155
	s_add_u32 s20, s22, 0x30000
	s_addc_u32 s21, s23, 0
	v_mul_f32_e32 v208, 0xbfb8aa3b, v110
	v_mul_f32_e32 v209, 0xbfb8aa3b, v111
	v_mul_f32_e32 v210, 0xbfb8aa3b, v112
	v_mul_f32_e32 v211, 0xbfb8aa3b, v113
	v_mul_f32_e32 v212, 0xbfb8aa3b, v106
	v_mul_f32_e32 v213, 0xbfb8aa3b, v107
	v_mul_f32_e32 v214, 0xbfb8aa3b, v108
	v_mul_f32_e32 v215, 0xbfb8aa3b, v109
	v_exp_f32_e32 v208, v208
	v_exp_f32_e32 v209, v209
	v_exp_f32_e32 v210, v210
	v_exp_f32_e32 v211, v211
	v_exp_f32_e32 v212, v212
	v_exp_f32_e32 v213, v213
	v_exp_f32_e32 v214, v214
	v_exp_f32_e32 v215, v215
	v_add_f32_e32 v208, 1.0, v208
	v_add_f32_e32 v209, 1.0, v209
	v_add_f32_e32 v210, 1.0, v210
	v_add_f32_e32 v211, 1.0, v211
	v_add_f32_e32 v212, 1.0, v212
	v_add_f32_e32 v213, 1.0, v213
	v_add_f32_e32 v214, 1.0, v214
	v_add_f32_e32 v215, 1.0, v215
	v_rcp_f32_e32 v208, v208
	v_rcp_f32_e32 v209, v209
	v_rcp_f32_e32 v210, v210
	v_rcp_f32_e32 v211, v211
	v_rcp_f32_e32 v212, v212
	v_rcp_f32_e32 v213, v213
	v_rcp_f32_e32 v214, v214
	v_rcp_f32_e32 v215, v215
	v_cvt_pk_bf16_f32 v156, v208, v209
	v_cvt_pk_bf16_f32 v157, v210, v211
	v_cvt_pk_bf16_f32 v158, v212, v213
	v_cvt_pk_bf16_f32 v159, v214, v215
	ds_bpermute_b32 v246, v217, v156
	ds_bpermute_b32 v247, v217, v157
	ds_bpermute_b32 v248, v217, v158
	ds_bpermute_b32 v249, v217, v159
	v_mul_f32_e32 v208, 0xbfb8aa3b, v102
	v_mul_f32_e32 v209, 0xbfb8aa3b, v103
	v_mul_f32_e32 v210, 0xbfb8aa3b, v104
	v_mul_f32_e32 v211, 0xbfb8aa3b, v105
	v_mul_f32_e32 v212, 0xbfb8aa3b, v98
	v_mul_f32_e32 v213, 0xbfb8aa3b, v99
	v_mul_f32_e32 v214, 0xbfb8aa3b, v100
	v_mul_f32_e32 v215, 0xbfb8aa3b, v101
	v_exp_f32_e32 v208, v208
	v_exp_f32_e32 v209, v209
	v_exp_f32_e32 v210, v210
	v_exp_f32_e32 v211, v211
	v_exp_f32_e32 v212, v212
	v_exp_f32_e32 v213, v213
	v_exp_f32_e32 v214, v214
	v_exp_f32_e32 v215, v215
	v_add_f32_e32 v208, 1.0, v208
	v_add_f32_e32 v209, 1.0, v209
	v_add_f32_e32 v210, 1.0, v210
	v_add_f32_e32 v211, 1.0, v211
	v_add_f32_e32 v212, 1.0, v212
	v_add_f32_e32 v213, 1.0, v213
	v_add_f32_e32 v214, 1.0, v214
	v_add_f32_e32 v215, 1.0, v215
	v_rcp_f32_e32 v208, v208
	v_rcp_f32_e32 v209, v209
	v_rcp_f32_e32 v210, v210
	v_rcp_f32_e32 v211, v211
	v_rcp_f32_e32 v212, v212
	v_rcp_f32_e32 v213, v213
	v_rcp_f32_e32 v214, v214
	v_rcp_f32_e32 v215, v215
	v_cvt_pk_bf16_f32 v160, v208, v209
	v_cvt_pk_bf16_f32 v161, v210, v211
	v_cvt_pk_bf16_f32 v162, v212, v213
	v_cvt_pk_bf16_f32 v163, v214, v215
	ds_bpermute_b32 v250, v217, v160
	ds_bpermute_b32 v251, v217, v161
	ds_bpermute_b32 v252, v217, v162
	ds_bpermute_b32 v253, v217, v163
	s_waitcnt lgkmcnt(0)
	global_store_dwordx4 v235, v[238:241], s[10:11] sc0 sc1
	global_store_dwordx4 v235, v[242:245], s[10:11] offset:256 sc0 sc1
	global_store_dwordx4 v235, v[246:249], s[20:21] sc0 sc1
	global_store_dwordx4 v235, v[250:253], s[20:21] offset:256 sc0 sc1
	s_add_u32 s10, s22, 0x60000
	s_addc_u32 s11, s23, 0
	v_mul_f32_e32 v208, 0xbfb8aa3b, v94
	v_mul_f32_e32 v209, 0xbfb8aa3b, v95
	v_mul_f32_e32 v210, 0xbfb8aa3b, v96
	v_mul_f32_e32 v211, 0xbfb8aa3b, v97
	v_mul_f32_e32 v212, 0xbfb8aa3b, v90
	v_mul_f32_e32 v213, 0xbfb8aa3b, v91
	v_mul_f32_e32 v214, 0xbfb8aa3b, v92
	v_mul_f32_e32 v215, 0xbfb8aa3b, v93
	v_exp_f32_e32 v208, v208
	v_exp_f32_e32 v209, v209
	v_exp_f32_e32 v210, v210
	v_exp_f32_e32 v211, v211
	v_exp_f32_e32 v212, v212
	v_exp_f32_e32 v213, v213
	v_exp_f32_e32 v214, v214
	v_exp_f32_e32 v215, v215
	v_add_f32_e32 v208, 1.0, v208
	v_add_f32_e32 v209, 1.0, v209
	v_add_f32_e32 v210, 1.0, v210
	v_add_f32_e32 v211, 1.0, v211
	v_add_f32_e32 v212, 1.0, v212
	v_add_f32_e32 v213, 1.0, v213
	v_add_f32_e32 v214, 1.0, v214
	v_add_f32_e32 v215, 1.0, v215
	v_rcp_f32_e32 v208, v208
	v_rcp_f32_e32 v209, v209
	v_rcp_f32_e32 v210, v210
	v_rcp_f32_e32 v211, v211
	v_rcp_f32_e32 v212, v212
	v_rcp_f32_e32 v213, v213
	v_rcp_f32_e32 v214, v214
	v_rcp_f32_e32 v215, v215
	v_cvt_pk_bf16_f32 v148, v208, v209
	v_cvt_pk_bf16_f32 v149, v210, v211
	v_cvt_pk_bf16_f32 v150, v212, v213
	v_cvt_pk_bf16_f32 v151, v214, v215
	ds_bpermute_b32 v238, v217, v148
	ds_bpermute_b32 v239, v217, v149
	ds_bpermute_b32 v240, v217, v150
	ds_bpermute_b32 v241, v217, v151
	v_mul_f32_e32 v208, 0xbfb8aa3b, v86
	v_mul_f32_e32 v209, 0xbfb8aa3b, v87
	v_mul_f32_e32 v210, 0xbfb8aa3b, v88
	v_mul_f32_e32 v211, 0xbfb8aa3b, v89
	v_mul_f32_e32 v212, 0xbfb8aa3b, v82
	v_mul_f32_e32 v213, 0xbfb8aa3b, v83
	v_mul_f32_e32 v214, 0xbfb8aa3b, v84
	v_mul_f32_e32 v215, 0xbfb8aa3b, v85
	v_exp_f32_e32 v208, v208
	v_exp_f32_e32 v209, v209
	v_exp_f32_e32 v210, v210
	v_exp_f32_e32 v211, v211
	v_exp_f32_e32 v212, v212
	v_exp_f32_e32 v213, v213
	v_exp_f32_e32 v214, v214
	v_exp_f32_e32 v215, v215
	v_add_f32_e32 v208, 1.0, v208
	v_add_f32_e32 v209, 1.0, v209
	v_add_f32_e32 v210, 1.0, v210
	v_add_f32_e32 v211, 1.0, v211
	v_add_f32_e32 v212, 1.0, v212
	v_add_f32_e32 v213, 1.0, v213
	v_add_f32_e32 v214, 1.0, v214
	v_add_f32_e32 v215, 1.0, v215
	v_rcp_f32_e32 v208, v208
	v_rcp_f32_e32 v209, v209
	v_rcp_f32_e32 v210, v210
	v_rcp_f32_e32 v211, v211
	v_rcp_f32_e32 v212, v212
	v_rcp_f32_e32 v213, v213
	v_rcp_f32_e32 v214, v214
	v_rcp_f32_e32 v215, v215
	v_cvt_pk_bf16_f32 v152, v208, v209
	v_cvt_pk_bf16_f32 v153, v210, v211
	v_cvt_pk_bf16_f32 v154, v212, v213
	v_cvt_pk_bf16_f32 v155, v214, v215
	ds_bpermute_b32 v242, v217, v152
	ds_bpermute_b32 v243, v217, v153
	ds_bpermute_b32 v244, v217, v154
	ds_bpermute_b32 v245, v217, v155
	s_add_u32 s20, s22, 0x90000
	s_addc_u32 s21, s23, 0
	v_mul_f32_e32 v208, 0xbfb8aa3b, v78
	v_mul_f32_e32 v209, 0xbfb8aa3b, v79
	v_mul_f32_e32 v210, 0xbfb8aa3b, v80
	v_mul_f32_e32 v211, 0xbfb8aa3b, v81
	v_mul_f32_e32 v212, 0xbfb8aa3b, v74
	v_mul_f32_e32 v213, 0xbfb8aa3b, v75
	v_mul_f32_e32 v214, 0xbfb8aa3b, v76
	v_mul_f32_e32 v215, 0xbfb8aa3b, v77
	v_exp_f32_e32 v208, v208
	v_exp_f32_e32 v209, v209
	v_exp_f32_e32 v210, v210
	v_exp_f32_e32 v211, v211
	v_exp_f32_e32 v212, v212
	v_exp_f32_e32 v213, v213
	v_exp_f32_e32 v214, v214
	v_exp_f32_e32 v215, v215
	v_add_f32_e32 v208, 1.0, v208
	v_add_f32_e32 v209, 1.0, v209
	v_add_f32_e32 v210, 1.0, v210
	v_add_f32_e32 v211, 1.0, v211
	v_add_f32_e32 v212, 1.0, v212
	v_add_f32_e32 v213, 1.0, v213
	v_add_f32_e32 v214, 1.0, v214
	v_add_f32_e32 v215, 1.0, v215
	v_rcp_f32_e32 v208, v208
	v_rcp_f32_e32 v209, v209
	v_rcp_f32_e32 v210, v210
	v_rcp_f32_e32 v211, v211
	v_rcp_f32_e32 v212, v212
	v_rcp_f32_e32 v213, v213
	v_rcp_f32_e32 v214, v214
	v_rcp_f32_e32 v215, v215
	v_cvt_pk_bf16_f32 v156, v208, v209
	v_cvt_pk_bf16_f32 v157, v210, v211
	v_cvt_pk_bf16_f32 v158, v212, v213
	v_cvt_pk_bf16_f32 v159, v214, v215
	ds_bpermute_b32 v246, v217, v156
	ds_bpermute_b32 v247, v217, v157
	ds_bpermute_b32 v248, v217, v158
	ds_bpermute_b32 v249, v217, v159
	v_mul_f32_e32 v208, 0xbfb8aa3b, v70
	v_mul_f32_e32 v209, 0xbfb8aa3b, v71
	v_mul_f32_e32 v210, 0xbfb8aa3b, v72
	v_mul_f32_e32 v211, 0xbfb8aa3b, v73
	v_mul_f32_e32 v212, 0xbfb8aa3b, v66
	v_mul_f32_e32 v213, 0xbfb8aa3b, v67
	v_mul_f32_e32 v214, 0xbfb8aa3b, v68
	v_mul_f32_e32 v215, 0xbfb8aa3b, v69
	v_exp_f32_e32 v208, v208
	v_exp_f32_e32 v209, v209
	v_exp_f32_e32 v210, v210
	v_exp_f32_e32 v211, v211
	v_exp_f32_e32 v212, v212
	v_exp_f32_e32 v213, v213
	v_exp_f32_e32 v214, v214
	v_exp_f32_e32 v215, v215
	v_add_f32_e32 v208, 1.0, v208
	v_add_f32_e32 v209, 1.0, v209
	v_add_f32_e32 v210, 1.0, v210
	v_add_f32_e32 v211, 1.0, v211
	v_add_f32_e32 v212, 1.0, v212
	v_add_f32_e32 v213, 1.0, v213
	v_add_f32_e32 v214, 1.0, v214
	v_add_f32_e32 v215, 1.0, v215
	v_rcp_f32_e32 v208, v208
	v_rcp_f32_e32 v209, v209
	v_rcp_f32_e32 v210, v210
	v_rcp_f32_e32 v211, v211
	v_rcp_f32_e32 v212, v212
	v_rcp_f32_e32 v213, v213
	v_rcp_f32_e32 v214, v214
	v_rcp_f32_e32 v215, v215
	v_cvt_pk_bf16_f32 v160, v208, v209
	v_cvt_pk_bf16_f32 v161, v210, v211
	v_cvt_pk_bf16_f32 v162, v212, v213
	v_cvt_pk_bf16_f32 v163, v214, v215
	ds_bpermute_b32 v250, v217, v160
	ds_bpermute_b32 v251, v217, v161
	ds_bpermute_b32 v252, v217, v162
	ds_bpermute_b32 v253, v217, v163
	s_waitcnt lgkmcnt(0)
	global_store_dwordx4 v235, v[238:241], s[10:11] sc0 sc1
	global_store_dwordx4 v235, v[242:245], s[10:11] offset:256 sc0 sc1
	global_store_dwordx4 v235, v[246:249], s[20:21] sc0 sc1
	global_store_dwordx4 v235, v[250:253], s[20:21] offset:256 sc0 sc1
	s_add_u32 s10, s22, 0x180000
	s_addc_u32 s11, s23, 0
	v_mul_f32_e32 v208, 0xbfb8aa3b, v62
	v_mul_f32_e32 v209, 0xbfb8aa3b, v63
	v_mul_f32_e32 v210, 0xbfb8aa3b, v64
	v_mul_f32_e32 v211, 0xbfb8aa3b, v65
	v_mul_f32_e32 v212, 0xbfb8aa3b, v58
	v_mul_f32_e32 v213, 0xbfb8aa3b, v59
	v_mul_f32_e32 v214, 0xbfb8aa3b, v60
	v_mul_f32_e32 v215, 0xbfb8aa3b, v61
	v_exp_f32_e32 v208, v208
	v_exp_f32_e32 v209, v209
	v_exp_f32_e32 v210, v210
	v_exp_f32_e32 v211, v211
	v_exp_f32_e32 v212, v212
	v_exp_f32_e32 v213, v213
	v_exp_f32_e32 v214, v214
	v_exp_f32_e32 v215, v215
	v_add_f32_e32 v208, 1.0, v208
	v_add_f32_e32 v209, 1.0, v209
	v_add_f32_e32 v210, 1.0, v210
	v_add_f32_e32 v211, 1.0, v211
	v_add_f32_e32 v212, 1.0, v212
	v_add_f32_e32 v213, 1.0, v213
	v_add_f32_e32 v214, 1.0, v214
	v_add_f32_e32 v215, 1.0, v215
	v_rcp_f32_e32 v208, v208
	v_rcp_f32_e32 v209, v209
	v_rcp_f32_e32 v210, v210
	v_rcp_f32_e32 v211, v211
	v_rcp_f32_e32 v212, v212
	v_rcp_f32_e32 v213, v213
	v_rcp_f32_e32 v214, v214
	v_rcp_f32_e32 v215, v215
	v_cvt_pk_bf16_f32 v148, v208, v209
	v_cvt_pk_bf16_f32 v149, v210, v211
	v_cvt_pk_bf16_f32 v150, v212, v213
	v_cvt_pk_bf16_f32 v151, v214, v215
	ds_bpermute_b32 v238, v217, v148
	ds_bpermute_b32 v239, v217, v149
	ds_bpermute_b32 v240, v217, v150
	ds_bpermute_b32 v241, v217, v151
	v_mul_f32_e32 v208, 0xbfb8aa3b, v54
	v_mul_f32_e32 v209, 0xbfb8aa3b, v55
	v_mul_f32_e32 v210, 0xbfb8aa3b, v56
	v_mul_f32_e32 v211, 0xbfb8aa3b, v57
	v_mul_f32_e32 v212, 0xbfb8aa3b, v50
	v_mul_f32_e32 v213, 0xbfb8aa3b, v51
	v_mul_f32_e32 v214, 0xbfb8aa3b, v52
	v_mul_f32_e32 v215, 0xbfb8aa3b, v53
	v_exp_f32_e32 v208, v208
	v_exp_f32_e32 v209, v209
	v_exp_f32_e32 v210, v210
	v_exp_f32_e32 v211, v211
	v_exp_f32_e32 v212, v212
	v_exp_f32_e32 v213, v213
	v_exp_f32_e32 v214, v214
	v_exp_f32_e32 v215, v215
	v_add_f32_e32 v208, 1.0, v208
	v_add_f32_e32 v209, 1.0, v209
	v_add_f32_e32 v210, 1.0, v210
	v_add_f32_e32 v211, 1.0, v211
	v_add_f32_e32 v212, 1.0, v212
	v_add_f32_e32 v213, 1.0, v213
	v_add_f32_e32 v214, 1.0, v214
	v_add_f32_e32 v215, 1.0, v215
	v_rcp_f32_e32 v208, v208
	v_rcp_f32_e32 v209, v209
	v_rcp_f32_e32 v210, v210
	v_rcp_f32_e32 v211, v211
	v_rcp_f32_e32 v212, v212
	v_rcp_f32_e32 v213, v213
	v_rcp_f32_e32 v214, v214
	v_rcp_f32_e32 v215, v215
	v_cvt_pk_bf16_f32 v152, v208, v209
	v_cvt_pk_bf16_f32 v153, v210, v211
	v_cvt_pk_bf16_f32 v154, v212, v213
	v_cvt_pk_bf16_f32 v155, v214, v215
	ds_bpermute_b32 v242, v217, v152
	ds_bpermute_b32 v243, v217, v153
	ds_bpermute_b32 v244, v217, v154
	ds_bpermute_b32 v245, v217, v155
	s_add_u32 s20, s22, 0x1b0000
	s_addc_u32 s21, s23, 0
	v_mul_f32_e32 v208, 0xbfb8aa3b, v46
	v_mul_f32_e32 v209, 0xbfb8aa3b, v47
	v_mul_f32_e32 v210, 0xbfb8aa3b, v48
	v_mul_f32_e32 v211, 0xbfb8aa3b, v49
	v_mul_f32_e32 v212, 0xbfb8aa3b, v42
	v_mul_f32_e32 v213, 0xbfb8aa3b, v43
	v_mul_f32_e32 v214, 0xbfb8aa3b, v44
	v_mul_f32_e32 v215, 0xbfb8aa3b, v45
	v_exp_f32_e32 v208, v208
	v_exp_f32_e32 v209, v209
	v_exp_f32_e32 v210, v210
	v_exp_f32_e32 v211, v211
	v_exp_f32_e32 v212, v212
	v_exp_f32_e32 v213, v213
	v_exp_f32_e32 v214, v214
	v_exp_f32_e32 v215, v215
	v_add_f32_e32 v208, 1.0, v208
	v_add_f32_e32 v209, 1.0, v209
	v_add_f32_e32 v210, 1.0, v210
	v_add_f32_e32 v211, 1.0, v211
	v_add_f32_e32 v212, 1.0, v212
	v_add_f32_e32 v213, 1.0, v213
	v_add_f32_e32 v214, 1.0, v214
	v_add_f32_e32 v215, 1.0, v215
	v_rcp_f32_e32 v208, v208
	v_rcp_f32_e32 v209, v209
	v_rcp_f32_e32 v210, v210
	v_rcp_f32_e32 v211, v211
	v_rcp_f32_e32 v212, v212
	v_rcp_f32_e32 v213, v213
	v_rcp_f32_e32 v214, v214
	v_rcp_f32_e32 v215, v215
	v_cvt_pk_bf16_f32 v156, v208, v209
	v_cvt_pk_bf16_f32 v157, v210, v211
	v_cvt_pk_bf16_f32 v158, v212, v213
	v_cvt_pk_bf16_f32 v159, v214, v215
	ds_bpermute_b32 v246, v217, v156
	ds_bpermute_b32 v247, v217, v157
	ds_bpermute_b32 v248, v217, v158
	ds_bpermute_b32 v249, v217, v159
	v_mul_f32_e32 v208, 0xbfb8aa3b, v38
	v_mul_f32_e32 v209, 0xbfb8aa3b, v39
	v_mul_f32_e32 v210, 0xbfb8aa3b, v40
	v_mul_f32_e32 v211, 0xbfb8aa3b, v41
	v_mul_f32_e32 v212, 0xbfb8aa3b, v34
	v_mul_f32_e32 v213, 0xbfb8aa3b, v35
	v_mul_f32_e32 v214, 0xbfb8aa3b, v36
	v_mul_f32_e32 v215, 0xbfb8aa3b, v37
	v_exp_f32_e32 v208, v208
	v_exp_f32_e32 v209, v209
	v_exp_f32_e32 v210, v210
	v_exp_f32_e32 v211, v211
	v_exp_f32_e32 v212, v212
	v_exp_f32_e32 v213, v213
	v_exp_f32_e32 v214, v214
	v_exp_f32_e32 v215, v215
	v_add_f32_e32 v208, 1.0, v208
	v_add_f32_e32 v209, 1.0, v209
	v_add_f32_e32 v210, 1.0, v210
	v_add_f32_e32 v211, 1.0, v211
	v_add_f32_e32 v212, 1.0, v212
	v_add_f32_e32 v213, 1.0, v213
	v_add_f32_e32 v214, 1.0, v214
	v_add_f32_e32 v215, 1.0, v215
	v_rcp_f32_e32 v208, v208
	v_rcp_f32_e32 v209, v209
	v_rcp_f32_e32 v210, v210
	v_rcp_f32_e32 v211, v211
	v_rcp_f32_e32 v212, v212
	v_rcp_f32_e32 v213, v213
	v_rcp_f32_e32 v214, v214
	v_rcp_f32_e32 v215, v215
	v_cvt_pk_bf16_f32 v160, v208, v209
	v_cvt_pk_bf16_f32 v161, v210, v211
	v_cvt_pk_bf16_f32 v162, v212, v213
	v_cvt_pk_bf16_f32 v163, v214, v215
	ds_bpermute_b32 v250, v217, v160
	ds_bpermute_b32 v251, v217, v161
	ds_bpermute_b32 v252, v217, v162
	ds_bpermute_b32 v253, v217, v163
	s_waitcnt lgkmcnt(0)
	global_store_dwordx4 v235, v[238:241], s[10:11] sc0 sc1
	global_store_dwordx4 v235, v[242:245], s[10:11] offset:256 sc0 sc1
	global_store_dwordx4 v235, v[246:249], s[20:21] sc0 sc1
	global_store_dwordx4 v235, v[250:253], s[20:21] offset:256 sc0 sc1
	s_add_u32 s10, s22, 0x1e0000
	s_addc_u32 s11, s23, 0
	v_mul_f32_e32 v208, 0xbfb8aa3b, v28
	v_mul_f32_e32 v209, 0xbfb8aa3b, v29
	v_mul_f32_e32 v210, 0xbfb8aa3b, v30
	v_mul_f32_e32 v211, 0xbfb8aa3b, v31
	v_mul_f32_e32 v212, 0xbfb8aa3b, v24
	v_mul_f32_e32 v213, 0xbfb8aa3b, v25
	v_mul_f32_e32 v214, 0xbfb8aa3b, v26
	v_mul_f32_e32 v215, 0xbfb8aa3b, v27
	v_exp_f32_e32 v208, v208
	v_exp_f32_e32 v209, v209
	v_exp_f32_e32 v210, v210
	v_exp_f32_e32 v211, v211
	v_exp_f32_e32 v212, v212
	v_exp_f32_e32 v213, v213
	v_exp_f32_e32 v214, v214
	v_exp_f32_e32 v215, v215
	v_add_f32_e32 v208, 1.0, v208
	v_add_f32_e32 v209, 1.0, v209
	v_add_f32_e32 v210, 1.0, v210
	v_add_f32_e32 v211, 1.0, v211
	v_add_f32_e32 v212, 1.0, v212
	v_add_f32_e32 v213, 1.0, v213
	v_add_f32_e32 v214, 1.0, v214
	v_add_f32_e32 v215, 1.0, v215
	v_rcp_f32_e32 v208, v208
	v_rcp_f32_e32 v209, v209
	v_rcp_f32_e32 v210, v210
	v_rcp_f32_e32 v211, v211
	v_rcp_f32_e32 v212, v212
	v_rcp_f32_e32 v213, v213
	v_rcp_f32_e32 v214, v214
	v_rcp_f32_e32 v215, v215
	v_cvt_pk_bf16_f32 v148, v208, v209
	v_cvt_pk_bf16_f32 v149, v210, v211
	v_cvt_pk_bf16_f32 v150, v212, v213
	v_cvt_pk_bf16_f32 v151, v214, v215
	ds_bpermute_b32 v238, v217, v148
	ds_bpermute_b32 v239, v217, v149
	ds_bpermute_b32 v240, v217, v150
	ds_bpermute_b32 v241, v217, v151
	v_mul_f32_e32 v208, 0xbfb8aa3b, v20
	v_mul_f32_e32 v209, 0xbfb8aa3b, v21
	v_mul_f32_e32 v210, 0xbfb8aa3b, v22
	v_mul_f32_e32 v211, 0xbfb8aa3b, v23
	v_mul_f32_e32 v212, 0xbfb8aa3b, v16
	v_mul_f32_e32 v213, 0xbfb8aa3b, v17
	v_mul_f32_e32 v214, 0xbfb8aa3b, v18
	v_mul_f32_e32 v215, 0xbfb8aa3b, v19
	v_exp_f32_e32 v208, v208
	v_exp_f32_e32 v209, v209
	v_exp_f32_e32 v210, v210
	v_exp_f32_e32 v211, v211
	v_exp_f32_e32 v212, v212
	v_exp_f32_e32 v213, v213
	v_exp_f32_e32 v214, v214
	v_exp_f32_e32 v215, v215
	v_add_f32_e32 v208, 1.0, v208
	v_add_f32_e32 v209, 1.0, v209
	v_add_f32_e32 v210, 1.0, v210
	v_add_f32_e32 v211, 1.0, v211
	v_add_f32_e32 v212, 1.0, v212
	v_add_f32_e32 v213, 1.0, v213
	v_add_f32_e32 v214, 1.0, v214
	v_add_f32_e32 v215, 1.0, v215
	v_rcp_f32_e32 v208, v208
	v_rcp_f32_e32 v209, v209
	v_rcp_f32_e32 v210, v210
	v_rcp_f32_e32 v211, v211
	v_rcp_f32_e32 v212, v212
	v_rcp_f32_e32 v213, v213
	v_rcp_f32_e32 v214, v214
	v_rcp_f32_e32 v215, v215
	v_cvt_pk_bf16_f32 v152, v208, v209
	v_cvt_pk_bf16_f32 v153, v210, v211
	v_cvt_pk_bf16_f32 v154, v212, v213
	v_cvt_pk_bf16_f32 v155, v214, v215
	ds_bpermute_b32 v242, v217, v152
	ds_bpermute_b32 v243, v217, v153
	ds_bpermute_b32 v244, v217, v154
	ds_bpermute_b32 v245, v217, v155
	s_add_u32 s20, s22, 0x210000
	s_addc_u32 s21, s23, 0
	v_mul_f32_e32 v208, 0xbfb8aa3b, v12
	v_mul_f32_e32 v209, 0xbfb8aa3b, v13
	v_mul_f32_e32 v210, 0xbfb8aa3b, v14
	v_mul_f32_e32 v211, 0xbfb8aa3b, v15
	v_mul_f32_e32 v212, 0xbfb8aa3b, v8
	v_mul_f32_e32 v213, 0xbfb8aa3b, v9
	v_mul_f32_e32 v214, 0xbfb8aa3b, v10
	v_mul_f32_e32 v215, 0xbfb8aa3b, v11
	v_exp_f32_e32 v208, v208
	v_exp_f32_e32 v209, v209
	v_exp_f32_e32 v210, v210
	v_exp_f32_e32 v211, v211
	v_exp_f32_e32 v212, v212
	v_exp_f32_e32 v213, v213
	v_exp_f32_e32 v214, v214
	v_exp_f32_e32 v215, v215
	v_add_f32_e32 v208, 1.0, v208
	v_add_f32_e32 v209, 1.0, v209
	v_add_f32_e32 v210, 1.0, v210
	v_add_f32_e32 v211, 1.0, v211
	v_add_f32_e32 v212, 1.0, v212
	v_add_f32_e32 v213, 1.0, v213
	v_add_f32_e32 v214, 1.0, v214
	v_add_f32_e32 v215, 1.0, v215
	v_rcp_f32_e32 v208, v208
	v_rcp_f32_e32 v209, v209
	v_rcp_f32_e32 v210, v210
	v_rcp_f32_e32 v211, v211
	v_rcp_f32_e32 v212, v212
	v_rcp_f32_e32 v213, v213
	v_rcp_f32_e32 v214, v214
	v_rcp_f32_e32 v215, v215
	v_cvt_pk_bf16_f32 v156, v208, v209
	v_cvt_pk_bf16_f32 v157, v210, v211
	v_cvt_pk_bf16_f32 v158, v212, v213
	v_cvt_pk_bf16_f32 v159, v214, v215
	ds_bpermute_b32 v246, v217, v156
	ds_bpermute_b32 v247, v217, v157
	ds_bpermute_b32 v248, v217, v158
	ds_bpermute_b32 v249, v217, v159
	v_mul_f32_e32 v208, 0xbfb8aa3b, v4
	v_mul_f32_e32 v209, 0xbfb8aa3b, v5
	v_mul_f32_e32 v210, 0xbfb8aa3b, v6
	v_mul_f32_e32 v211, 0xbfb8aa3b, v7
	v_mul_f32_e32 v212, 0xbfb8aa3b, v0
	v_mul_f32_e32 v213, 0xbfb8aa3b, v1
	v_mul_f32_e32 v214, 0xbfb8aa3b, v2
	v_mul_f32_e32 v215, 0xbfb8aa3b, v3
	v_exp_f32_e32 v208, v208
	v_exp_f32_e32 v209, v209
	v_exp_f32_e32 v210, v210
	v_exp_f32_e32 v211, v211
	v_exp_f32_e32 v212, v212
	v_exp_f32_e32 v213, v213
	v_exp_f32_e32 v214, v214
	v_exp_f32_e32 v215, v215
	v_add_f32_e32 v208, 1.0, v208
	v_add_f32_e32 v209, 1.0, v209
	v_add_f32_e32 v210, 1.0, v210
	v_add_f32_e32 v211, 1.0, v211
	v_add_f32_e32 v212, 1.0, v212
	v_add_f32_e32 v213, 1.0, v213
	v_add_f32_e32 v214, 1.0, v214
	v_add_f32_e32 v215, 1.0, v215
	v_rcp_f32_e32 v208, v208
	v_rcp_f32_e32 v209, v209
	v_rcp_f32_e32 v210, v210
	v_rcp_f32_e32 v211, v211
	v_rcp_f32_e32 v212, v212
	v_rcp_f32_e32 v213, v213
	v_rcp_f32_e32 v214, v214
	v_rcp_f32_e32 v215, v215
	v_cvt_pk_bf16_f32 v160, v208, v209
	v_cvt_pk_bf16_f32 v161, v210, v211
	v_cvt_pk_bf16_f32 v162, v212, v213
	v_cvt_pk_bf16_f32 v163, v214, v215
	ds_bpermute_b32 v250, v217, v160
	ds_bpermute_b32 v251, v217, v161
	ds_bpermute_b32 v252, v217, v162
	ds_bpermute_b32 v253, v217, v163
	s_waitcnt lgkmcnt(0)
	global_store_dwordx4 v235, v[238:241], s[10:11] sc0 sc1
	global_store_dwordx4 v235, v[242:245], s[10:11] offset:256 sc0 sc1
	global_store_dwordx4 v235, v[246:249], s[20:21] sc0 sc1
	global_store_dwordx4 v235, v[250:253], s[20:21] offset:256 sc0 sc1
	s_mov_b32 s101, 0
	s_branch .Lmain_latch_fast

	.amdhsa_kernel _Z4mega6Params
		.amdhsa_group_segment_fixed_size 0
		.amdhsa_private_segment_fixed_size 0
		.amdhsa_kernarg_size 424
		.amdhsa_user_sgpr_count 2
		.amdhsa_user_sgpr_dispatch_ptr 0
		.amdhsa_user_sgpr_queue_ptr 0
		.amdhsa_user_sgpr_kernarg_segment_ptr 1
		.amdhsa_user_sgpr_dispatch_id 0
		.amdhsa_user_sgpr_kernarg_preload_length 0
		.amdhsa_user_sgpr_kernarg_preload_offset 0
		.amdhsa_user_sgpr_private_segment_size 0
		.amdhsa_uses_dynamic_stack 0
		.amdhsa_enable_private_segment 0
		.amdhsa_system_sgpr_workgroup_id_x 1
		.amdhsa_system_sgpr_workgroup_id_y 0
		.amdhsa_system_sgpr_workgroup_id_z 0
		.amdhsa_system_sgpr_workgroup_info 0
		.amdhsa_system_vgpr_workitem_id 2
		.amdhsa_next_free_vgpr 256
		.amdhsa_next_free_sgpr 102
		.amdhsa_accum_offset 256
		.amdhsa_reserve_vcc 1
		.amdhsa_float_round_mode_32 0
		.amdhsa_float_round_mode_16_64 0
		.amdhsa_float_denorm_mode_32 3
		.amdhsa_float_denorm_mode_16_64 3
		.amdhsa_dx10_clamp 1
		.amdhsa_ieee_mode 1
		.amdhsa_fp16_overflow 0
		.amdhsa_tg_split 0
		.amdhsa_exception_fp_ieee_invalid_op 0
		.amdhsa_exception_fp_denorm_src 0
		.amdhsa_exception_fp_ieee_div_zero 0
		.amdhsa_exception_fp_ieee_overflow 0
		.amdhsa_exception_fp_ieee_underflow 0
		.amdhsa_exception_fp_ieee_inexact 0
		.amdhsa_exception_int_div_zero 0
	.end_amdhsa_kernel

amdhsa.kernels:
  - .agpr_count:     0
    .args:
      - .offset:         0
        .size:           168
        .value_kind:     by_value
      - .offset:         168
        .size:           4
        .value_kind:     hidden_block_count_x
      - .offset:         172
        .size:           4
        .value_kind:     hidden_block_count_y
      - .offset:         176
        .size:           4
        .value_kind:     hidden_block_count_z
      - .offset:         180
        .size:           2
        .value_kind:     hidden_group_size_x
      - .offset:         182
        .size:           2
        .value_kind:     hidden_group_size_y
      - .offset:         184
        .size:           2
        .value_kind:     hidden_group_size_z
      - .offset:         186
        .size:           2
        .value_kind:     hidden_remainder_x
      - .offset:         188
        .size:           2
        .value_kind:     hidden_remainder_y
      - .offset:         190
        .size:           2
        .value_kind:     hidden_remainder_z
      - .offset:         208
        .size:           8
        .value_kind:     hidden_global_offset_x
      - .offset:         216
        .size:           8
        .value_kind:     hidden_global_offset_y
      - .offset:         224
        .size:           8
        .value_kind:     hidden_global_offset_z
      - .offset:         232
        .size:           2
        .value_kind:     hidden_grid_dims
      - .offset:         256
        .size:           8
        .value_kind:     hidden_multigrid_sync_arg
      - .offset:         288
        .size:           4
        .value_kind:     hidden_dynamic_lds_size
    .group_segment_fixed_size: 0
    .kernarg_segment_align: 8
    .kernarg_segment_size: 424
    .language:       OpenCL C
    .language_version:
      - 2
      - 0
    .max_flat_workgroup_size: 512
    .name:           _Z4mega6Params
    .private_segment_fixed_size: 0
    .sgpr_count:     108
    .sgpr_spill_count: 122
    .symbol:         _Z4mega6Params.kd
    .uniform_work_group_size: 1
    .uses_dynamic_stack: false
    .vgpr_count:     256
    .vgpr_spill_count: 0
    .wavefront_size: 64
